# MoBA home combine reads the partial slots with sc1 (L1-bypassing) loads instead of every wave invalidating the CU L1 each unit
# speedup vs baseline: 1.0190x; 1.0156x over previous
.LBB0_1962:
	s_waitcnt vmcnt(0)
	s_waitcnt lgkmcnt(0)
	s_barrier
	s_waitcnt vmcnt(7)
	v_mov_b32_e32 v2, v170
	v_mov_b32_e32 v3, v14
	s_waitcnt vmcnt(0)
	s_nop 0
	v_permlane32_swap_b32_e32 v14, v3
	v_lshl_add_u32 v4, v2, 1, v2
	v_add_f32_e32 v3, v14, v3
	v_cmp_ne_u32_sdwa s[20:21], v179, v167 src0_sel:BYTE_0 src1_sel:DWORD
	v_ashrrev_i32_e32 v5, 31, v4
	s_and_saveexec_b64 s[18:19], s[20:21]
	s_cbranch_execz .LBB0_1964
	v_lshlrev_b64 v[14:15], 2, v[4:5]
	v_lshl_add_u64 v[6:7], s[48:49], 0, v[14:15]
	global_load_dword v88, v[6:7], off sc1
	v_lshlrev_b64 v[6:7], 8, v[4:5]
	v_lshl_add_u64 v[84:85], v[172:173], 0, v[6:7]
	v_lshl_add_u64 v[14:15], s[46:47], 0, v[14:15]
	global_load_dwordx4 v[6:9], v[84:85], off sc1
	global_load_dwordx4 v[10:13], v[84:85], off offset:128 sc1
	global_load_dwordx4 v[64:67], v[84:85], off offset:32 sc1
	global_load_dwordx4 v[68:71], v[84:85], off offset:160 sc1
	global_load_dwordx4 v[72:75], v[84:85], off offset:64 sc1
	global_load_dwordx4 v[76:79], v[84:85], off offset:192 sc1
	global_load_dwordx4 v[80:83], v[84:85], off offset:96 sc1
	s_nop 0
	global_load_dwordx4 v[84:87], v[84:85], off offset:224 sc1
	s_nop 0
	global_load_dword v15, v[14:15], off sc1
	s_waitcnt vmcnt(9)
	v_sub_f32_e32 v14, v88, v1
	v_exp_f32_e32 v14, v14
	s_waitcnt vmcnt(0)
	v_pk_fma_f32 v[50:51], v[8:9], v[14:15], v[50:51] op_sel_hi:[1,0,1]
	v_pk_fma_f32 v[48:49], v[6:7], v[14:15], v[48:49] op_sel_hi:[1,0,1]
	v_pk_fma_f32 v[34:35], v[12:13], v[14:15], v[34:35] op_sel_hi:[1,0,1]
	v_pk_fma_f32 v[32:33], v[10:11], v[14:15], v[32:33] op_sel_hi:[1,0,1]
	v_pk_fma_f32 v[54:55], v[66:67], v[14:15], v[54:55] op_sel_hi:[1,0,1]
	v_pk_fma_f32 v[52:53], v[64:65], v[14:15], v[52:53] op_sel_hi:[1,0,1]
	v_pk_fma_f32 v[38:39], v[14:15], v[70:71], v[38:39] op_sel_hi:[0,1,1]
	v_pk_fma_f32 v[36:37], v[14:15], v[68:69], v[36:37] op_sel_hi:[0,1,1]
	v_pk_fma_f32 v[58:59], v[14:15], v[74:75], v[58:59] op_sel_hi:[0,1,1]
	v_pk_fma_f32 v[56:57], v[14:15], v[72:73], v[56:57] op_sel_hi:[0,1,1]
	v_pk_fma_f32 v[42:43], v[14:15], v[78:79], v[42:43] op_sel_hi:[0,1,1]
	v_pk_fma_f32 v[40:41], v[14:15], v[76:77], v[40:41] op_sel_hi:[0,1,1]
	v_pk_fma_f32 v[62:63], v[14:15], v[82:83], v[62:63] op_sel_hi:[0,1,1]
	v_pk_fma_f32 v[60:61], v[14:15], v[80:81], v[60:61] op_sel_hi:[0,1,1]
	v_pk_fma_f32 v[46:47], v[14:15], v[86:87], v[46:47] op_sel_hi:[0,1,1]
	v_pk_fma_f32 v[44:45], v[14:15], v[84:85], v[44:45] op_sel_hi:[0,1,1]
	v_fmac_f32_e32 v3, v14, v15
.LBB0_1964:
	s_or_b64 exec, exec, s[18:19]
	v_and_b32_e32 v6, 0xff00, v179
	v_cmp_ne_u32_e32 vcc, 0, v6
	s_and_saveexec_b64 s[18:19], vcc
	s_cbranch_execz .LBB0_1966
	v_lshlrev_b64 v[14:15], 2, v[4:5]
	v_lshl_add_u64 v[6:7], s[48:49], 0, v[14:15]
	global_load_dword v88, v[6:7], off offset:4 sc1
	v_lshlrev_b64 v[6:7], 8, v[4:5]
	v_lshl_add_u64 v[84:85], v[172:173], 0, v[6:7]
	v_lshl_add_u64 v[14:15], s[46:47], 0, v[14:15]
	global_load_dwordx4 v[6:9], v[84:85], off offset:256 sc1
	global_load_dwordx4 v[10:13], v[84:85], off offset:384 sc1
	global_load_dwordx4 v[64:67], v[84:85], off offset:288 sc1
	global_load_dwordx4 v[68:71], v[84:85], off offset:416 sc1
	global_load_dwordx4 v[72:75], v[84:85], off offset:320 sc1
	global_load_dwordx4 v[76:79], v[84:85], off offset:448 sc1
	global_load_dwordx4 v[80:83], v[84:85], off offset:352 sc1
	s_nop 0
	global_load_dwordx4 v[84:87], v[84:85], off offset:480 sc1
	s_nop 0
	global_load_dword v15, v[14:15], off offset:4 sc1
	s_waitcnt vmcnt(9)
	v_sub_f32_e32 v14, v88, v1
	v_exp_f32_e32 v14, v14
	s_waitcnt vmcnt(0)
	v_pk_fma_f32 v[50:51], v[8:9], v[14:15], v[50:51] op_sel_hi:[1,0,1]
	v_pk_fma_f32 v[48:49], v[6:7], v[14:15], v[48:49] op_sel_hi:[1,0,1]
	v_pk_fma_f32 v[34:35], v[12:13], v[14:15], v[34:35] op_sel_hi:[1,0,1]
	v_pk_fma_f32 v[32:33], v[10:11], v[14:15], v[32:33] op_sel_hi:[1,0,1]
	v_pk_fma_f32 v[54:55], v[66:67], v[14:15], v[54:55] op_sel_hi:[1,0,1]
	v_pk_fma_f32 v[52:53], v[64:65], v[14:15], v[52:53] op_sel_hi:[1,0,1]
	v_pk_fma_f32 v[38:39], v[14:15], v[70:71], v[38:39] op_sel_hi:[0,1,1]
	v_pk_fma_f32 v[36:37], v[14:15], v[68:69], v[36:37] op_sel_hi:[0,1,1]
	v_pk_fma_f32 v[58:59], v[14:15], v[74:75], v[58:59] op_sel_hi:[0,1,1]
	v_pk_fma_f32 v[56:57], v[14:15], v[72:73], v[56:57] op_sel_hi:[0,1,1]
	v_pk_fma_f32 v[42:43], v[14:15], v[78:79], v[42:43] op_sel_hi:[0,1,1]
	v_pk_fma_f32 v[40:41], v[14:15], v[76:77], v[40:41] op_sel_hi:[0,1,1]
	v_pk_fma_f32 v[62:63], v[14:15], v[82:83], v[62:63] op_sel_hi:[0,1,1]
	v_pk_fma_f32 v[60:61], v[14:15], v[80:81], v[60:61] op_sel_hi:[0,1,1]
	v_pk_fma_f32 v[46:47], v[14:15], v[86:87], v[46:47] op_sel_hi:[0,1,1]
	v_pk_fma_f32 v[44:45], v[14:15], v[84:85], v[44:45] op_sel_hi:[0,1,1]
	v_fmac_f32_e32 v3, v14, v15
.LBB0_1966:
	s_or_b64 exec, exec, s[18:19]
	v_and_b32_e32 v6, 0xff0000, v179
	v_cmp_ne_u32_e32 vcc, 0, v6
	s_and_saveexec_b64 s[18:19], vcc
	s_cbranch_execz .LBB0_1872
	v_lshlrev_b64 v[84:85], 2, v[4:5]
	v_lshl_add_u64 v[6:7], s[48:49], 0, v[84:85]
	global_load_dword v86, v[6:7], off offset:8 sc1
	v_lshlrev_b64 v[4:5], 8, v[4:5]
	v_lshl_add_u64 v[80:81], v[172:173], 0, v[4:5]
	v_lshl_add_u64 v[84:85], s[46:47], 0, v[84:85]
	global_load_dwordx4 v[4:7], v[80:81], off offset:512 sc1
	global_load_dwordx4 v[8:11], v[80:81], off offset:640 sc1
	global_load_dwordx4 v[12:15], v[80:81], off offset:544 sc1
	global_load_dwordx4 v[64:67], v[80:81], off offset:672 sc1
	global_load_dwordx4 v[68:71], v[80:81], off offset:576 sc1
	global_load_dwordx4 v[72:75], v[80:81], off offset:704 sc1
	global_load_dwordx4 v[76:79], v[80:81], off offset:608 sc1
	s_nop 0
	global_load_dwordx4 v[80:83], v[80:81], off offset:736 sc1
	s_waitcnt vmcnt(8)
	v_sub_f32_e32 v1, v86, v1
	global_load_dword v85, v[84:85], off offset:8 sc1
	v_exp_f32_e32 v84, v1
	s_waitcnt vmcnt(0)
	v_pk_fma_f32 v[50:51], v[6:7], v[84:85], v[50:51] op_sel_hi:[1,0,1]
	v_pk_fma_f32 v[48:49], v[4:5], v[84:85], v[48:49] op_sel_hi:[1,0,1]
	v_pk_fma_f32 v[34:35], v[10:11], v[84:85], v[34:35] op_sel_hi:[1,0,1]
	v_pk_fma_f32 v[32:33], v[8:9], v[84:85], v[32:33] op_sel_hi:[1,0,1]
	v_pk_fma_f32 v[54:55], v[14:15], v[84:85], v[54:55] op_sel_hi:[1,0,1]
	v_pk_fma_f32 v[52:53], v[12:13], v[84:85], v[52:53] op_sel_hi:[1,0,1]
	v_pk_fma_f32 v[38:39], v[84:85], v[66:67], v[38:39] op_sel_hi:[0,1,1]
	v_pk_fma_f32 v[36:37], v[84:85], v[64:65], v[36:37] op_sel_hi:[0,1,1]
	v_pk_fma_f32 v[58:59], v[84:85], v[70:71], v[58:59] op_sel_hi:[0,1,1]
	v_pk_fma_f32 v[56:57], v[84:85], v[68:69], v[56:57] op_sel_hi:[0,1,1]
	v_pk_fma_f32 v[42:43], v[84:85], v[74:75], v[42:43] op_sel_hi:[0,1,1]
	v_pk_fma_f32 v[40:41], v[84:85], v[72:73], v[40:41] op_sel_hi:[0,1,1]
	v_pk_fma_f32 v[62:63], v[84:85], v[78:79], v[62:63] op_sel_hi:[0,1,1]
	v_pk_fma_f32 v[60:61], v[84:85], v[76:77], v[60:61] op_sel_hi:[0,1,1]
	v_pk_fma_f32 v[46:47], v[84:85], v[82:83], v[46:47] op_sel_hi:[0,1,1]
	v_pk_fma_f32 v[44:45], v[84:85], v[80:81], v[44:45] op_sel_hi:[0,1,1]
	v_fmac_f32_e32 v3, v84, v85
	s_branch .LBB0_1872
